# as the previous stack, but the storing gate passes wait for all gate loads before their first store (counted waits only in the ratio passes)
# baseline (speedup 1.0000x reference)
.LBB0_754:
	global_load_dwordx2 v[238:239], v[180:181], off
	global_load_dwordx2 v[226:227], v[180:181], off offset:128
	global_load_dwordx2 v[224:225], v[152:153], off
	global_load_dwordx2 v[218:219], v[152:153], off offset:128
	global_load_dwordx2 v[214:215], v[160:161], off
	global_load_dwordx2 v[208:209], v[160:161], off offset:128
	global_load_dwordx2 v[204:205], v[164:165], off
	global_load_dwordx2 v[194:195], v[164:165], off offset:128
	global_load_dwordx2 v[190:191], v[170:171], off
	global_load_dwordx2 v[184:185], v[170:171], off offset:128
	global_load_dwordx2 v[180:181], v[174:175], off
	s_nop 0
	global_load_dwordx2 v[174:175], v[174:175], off offset:128
	s_nop 0
	global_load_dwordx2 v[170:171], v[228:229], off
	global_load_dwordx2 v[164:165], v[228:229], off offset:128
	global_load_dwordx2 v[160:161], v[230:231], off
	global_load_dwordx2 v[152:153], v[230:231], off offset:128
	s_xor_b64 s[0:1], s[14:15], -1
	v_cndmask_b32_e64 v3, 0, 1, s[0:1]
	v_cmp_ne_u32_e64 s[12:13], 1, v3
	s_andn2_b64 vcc, exec, s[0:1]
	s_mov_b64 s[14:15], -1
	s_cmp_lg_u32 s98, 0
	s_cbranch_scc1 .Lx_gw_r0
	s_waitcnt vmcnt(0)
	s_branch .Lx_gw_d0
.Lx_gw_r0:
	s_waitcnt vmcnt(15)
.Lx_gw_d0:
	v_cvt_f32_ubyte1_e32 v233, v238
	v_cvt_f32_ubyte0_e32 v232, v238
	v_cvt_f32_ubyte3_e32 v235, v238
	v_cvt_f32_ubyte2_e32 v234, v238
	v_cvt_f32_ubyte1_e32 v229, v239
	v_cvt_f32_ubyte0_e32 v228, v239
	v_cvt_f32_ubyte3_e32 v231, v239
	v_cvt_f32_ubyte2_e32 v230, v239
	s_cbranch_vccnz .LBB0_760
	v_mul_f32_e32 v3, 0x3b808081, v232
	v_mul_f32_e32 v157, 0x3b808081, v233
	v_mul_f32_e32 v169, 0x3b808081, v234
	v_mul_f32_e32 v198, 0x3b808081, v235
	v_mul_f32_e32 v149, v130, v3
	v_mul_f32_e32 v3, 0x3b808081, v228
	v_mul_f32_e32 v179, v131, v157
	v_mul_f32_e32 v157, 0x3b808081, v229
	v_mul_f32_e32 v189, v132, v169
	v_mul_f32_e32 v169, 0x3b808081, v230
	v_mul_f32_e32 v213, v133, v198
	v_mul_f32_e32 v198, 0x3b808081, v231
	v_mul_f32_e32 v3, v126, v3
	v_mul_f32_e32 v157, v127, v157
	v_mul_f32_e32 v169, v128, v169
	v_mul_f32_e32 v203, v129, v198
	s_and_b64 vcc, exec, s[36:37]
	s_cbranch_vccz .LBB0_757
	s_ashr_i32 s65, s64, 31
	s_lshl_b64 s[0:1], s[64:65], 21
	s_add_u32 s0, s77, s0
	s_addc_u32 s1, s78, s1
	v_lshlrev_b64 v[198:199], 12, v[220:221]
	v_lshl_add_u64 v[198:199], s[0:1], 0, v[198:199]
	v_lshl_add_u64 v[198:199], v[4:5], 1, v[198:199]
	v_add_co_u32_e32 v198, vcc, 0xfe000000, v198
	v_cvt_pk_bf16_f32 v238, v149, v179
	v_cvt_pk_bf16_f32 v239, v189, v213
	v_cvt_pk_bf16_f32 v240, v3, v157
	v_cvt_pk_bf16_f32 v241, v169, v203
	s_nop 1
	v_addc_co_u32_e32 v199, vcc, -1, v199, vcc
	global_store_dwordx4 v[198:199], v[238:241], off
	s_mov_b64 s[14:15], 0
